# k16 + one static s_setprio 1 for waves 0-3 during the L0 attention and MLA attention phases (reset to 0 at phase end)
# speedup vs baseline: 1.0167x; 1.0052x over previous
; __global__ void __launch_bounds__(512, 2) fwd_kernel(Params P) {
;     ...
;                     { const bf16_t* QK = (const bf16_t*)(ws + WS_QK0); const bf16_t* VT = (const bf16_t*)(ws + WS_VT0);
;                       float la = IN(11)[lane] * IN(12)[lane], lb2 = IN(13)[lane] * IN(14)[lane];
;                       la = wave_sum(la); lb2 = wave_sum(lb2);
;                       const float lam = expf(la) - expf(lb2) + 0.2f;
.LBB0_563:
	v_readlane_b32 s0, v254, 8
	s_cmp_lt_i32 s0, 5
	s_cselect_b64 s[38:39], -1, 0
	s_and_b64 s[0:1], s[38:39], s[6:7]
	s_andn2_b64 vcc, exec, s[0:1]
	s_cbranch_vccnz .LBB0_638
	v_readlane_b32 s98, v254, 7
	s_nop 3
	s_cmp_lt_u32 s98, 4
	s_cbranch_scc0 .Lk16_prio_l0
	s_setprio 1

; __global__ void __launch_bounds__(512, 2) fwd_kernel(Params P) {
;     ...
;                     { const bf16_t* Q1 = (const bf16_t*)(ws + WS_Q1); const bf16_t* K1 = (const bf16_t*)(ws + WS_K1); const bf16_t* VT = (const bf16_t*)(ws + WS_VT1);
;                       for (int rep = 0; rep < REP_ATT; ++rep) for (int r = 0;; ++r) { const int u = SNAKE(r); if (u >= 2048) break;
;                           const int qb = 15 - (u >> 7), bh = u & 127, b = bh >> 4, h = bh & 15;
;                           attn_unit<96, 64, 0, 3, false>(lds, Q1 + (size_t)b * SEQ * 1536 + h * 96, 1536, K1 + (size_t)b * SEQ * 1536 + h * 96, 1536,
;                                                VT + (size_t)(h * 64) * MTOK + (size_t)b * SEQ, MTOK, (bf16_t*)(ws + WS_O1) + (size_t)b * SEQ * 1024 + h * 64, 1024,
;                                                qb * 256, qb * 4 + 4, 0.10206207261596575f * LOG2E, IN(22), nullptr, 0.f, 0.f, wave_s); } }
.LBB0_1633:
	v_readlane_b32 s0, v254, 8
	s_cmp_lt_i32 s0, 16
	s_cselect_b64 s[12:13], -1, 0
	s_and_b64 s[0:1], s[12:13], s[6:7]
	s_andn2_b64 vcc, exec, s[0:1]
	s_cbranch_vccnz .LBB0_1727
	s_cmpk_gt_i32 s88, 0x7ff
	v_mbcnt_lo_u32_b32 v0, -1, 0
	v_mbcnt_hi_u32_b32 v0, -1, v0
	s_mov_b32 s14, 0
	s_cbranch_scc1 .LBB0_1727
	v_readlane_b32 s98, v254, 7
	s_nop 3
	s_cmp_lt_u32 s98, 4
	s_cbranch_scc0 .Lk16_prio_mla
	s_setprio 1
